# all workgroups (leaders too) wait on the cross-XCD arrival counter reaching (gen+1)*nx instead of a separate release word
# speedup vs baseline: 1.0052x; 1.0049x over previous
.LBB0_819:
	s_or_b64 exec, exec, s[12:13]
	v_cvt_f32_u32_e32 v5, v3
	s_waitcnt vmcnt(0)
	v_readfirstlane_b32 s0, v4
	v_sub_u32_e32 v4, 0, v3
	v_rcp_iflag_f32_e32 v5, v5
	v_add_u32_e32 v6, s0, v2
	v_mul_f32_e32 v5, 0x4f7ffffe, v5
	v_cvt_u32_f32_e32 v5, v5
	v_mul_lo_u32 v2, v4, v5
	v_mul_hi_u32 v2, v5, v2
	v_add_u32_e32 v2, v5, v2
	v_mul_hi_u32 v2, v6, v2
	v_mul_lo_u32 v4, v2, v3
	v_sub_u32_e32 v4, v6, v4
	v_add_u32_e32 v5, 1, v2
	v_cmp_ge_u32_e32 vcc, v4, v3
	s_nop 1
	v_cndmask_b32_e32 v2, v2, v5, vcc
	v_sub_u32_e32 v5, v4, v3
	v_cndmask_b32_e32 v4, v4, v5, vcc
	v_add_u32_e32 v5, 1, v2
	v_cmp_ge_u32_e32 vcc, v4, v3
	v_add_u32_e32 v4, 1, v6
	s_nop 0
	v_cndmask_b32_e32 v2, v2, v5, vcc
	v_mul_lo_u32 v5, v3, v2
	v_add_u32_e32 v3, v5, v3
	v_cmp_ne_u32_e32 vcc, v4, v3
	s_and_saveexec_b64 s[0:1], vcc
	s_xor_b64 s[10:11], exec, s[0:1]
	s_cbranch_execz .LBB0_833
	s_waitcnt lgkmcnt(0)
	v_mad_u32_u24 v7, v2, v1, v1
	s_add_u32 s14, s78, 0x24703400
	s_addc_u32 s15, s79, 0
	global_load_dword v1, v0, s[14:15] sc1
	s_waitcnt vmcnt(0)
	v_cmp_gt_u32_e32 vcc, v7, v1
	s_and_saveexec_b64 s[12:13], vcc
	s_cbranch_execz .LBB0_832
	s_mov_b32 s0, 1
	s_mov_b64 s[16:17], 0
	s_branch .LBB0_823

.LBB0_825:
	global_load_dword v1, v0, s[14:15] sc1
	s_add_i32 s0, s0, 1
	s_mov_b64 s[22:23], -1
	s_waitcnt vmcnt(0)
	v_cmp_le_u32_e32 vcc, v7, v1
	s_orn2_b64 s[20:21], vcc, exec
	s_branch .LBB0_822

.LBB0_836:
	s_or_b64 exec, exec, s[12:13]
	v_cvt_f32_u32_e32 v4, v1
	s_waitcnt vmcnt(0)
	v_readfirstlane_b32 s0, v3
	s_add_u32 s10, s78, 0x24703500
	s_addc_u32 s11, s79, 0
	v_rcp_iflag_f32_e32 v4, v4
	v_add_u32_e32 v2, s0, v2
	s_mov_b64 s[14:15], -1
	v_mul_f32_e32 v3, 0x4f7ffffe, v4
	v_cvt_u32_f32_e32 v3, v3
	v_sub_u32_e32 v4, 0, v1
	v_mul_lo_u32 v4, v4, v3
	v_mul_hi_u32 v4, v3, v4
	v_add_u32_e32 v3, v3, v4
	v_mul_hi_u32 v3, v2, v3
	v_mul_lo_u32 v4, v3, v1
	v_sub_u32_e32 v4, v2, v4
	v_add_u32_e32 v5, 1, v3
	v_cmp_ge_u32_e32 vcc, v4, v1
	v_add_u32_e32 v2, 1, v2
	s_nop 0
	v_cndmask_b32_e32 v3, v3, v5, vcc
	v_sub_u32_e32 v5, v4, v1
	v_cndmask_b32_e32 v4, v4, v5, vcc
	v_add_u32_e32 v5, 1, v3
	v_cmp_ge_u32_e32 vcc, v4, v1
	s_nop 1
	v_cndmask_b32_e32 v4, v3, v5, vcc
	v_mul_lo_u32 v3, v1, v4
	v_add_u32_e32 v1, v3, v1
	v_cmp_ne_u32_e32 vcc, v2, v1
	v_mov_b64_e32 v[2:3], s[10:11]
	s_and_saveexec_b64 s[12:13], vcc
	s_cbranch_execz .LBB0_848
	s_add_u32 s46, s78, 0x24703400
	s_addc_u32 s47, s79, 0
	global_load_dword v5, v0, s[46:47] sc1
	s_mov_b64 s[16:17], 0
	s_waitcnt vmcnt(0)
	v_cmp_gt_u32_e32 vcc, v1, v5
	s_and_saveexec_b64 s[14:15], vcc
	s_cbranch_execz .LBB0_847
	s_mov_b32 s0, 1
	s_branch .LBB0_840

.LBB0_842:
	global_load_dword v5, v0, s[46:47] sc1
	s_add_i32 s0, s0, 1
	s_mov_b64 s[22:23], -1
	s_waitcnt vmcnt(0)
	v_cmp_le_u32_e32 vcc, v1, v5
	s_orn2_b64 s[20:21], vcc, exec
	s_branch .LBB0_839
.LBB0_843:
	global_load_dword v5, v0, s[6:7] sc1
	s_waitcnt vmcnt(0)
	v_cmp_eq_u32_e32 vcc, 0, v5
	s_cbranch_vccnz .LBB0_845
	s_mov_b64 s[22:23], -1
	s_branch .LBB0_839
